# bf16 residual epilogues (w2_0, wo1, w2_1): the 16 base pieces of a tile are loaded up front; the ladder only waits at its two gate loads
# speedup vs baseline: 1.0095x; 1.0031x over previous
; __device__ __forceinline__ unsigned cvt_pk_bf16(float lo, float hi) { unsigned r; asm volatile("v_cvt_pk_bf16_f32 %0, %1, %2" : "=v"(r) : "v"(lo), "v"(hi)); return r; }
;     __device__ __forceinline__ void operator()(const f32x4 (&acc)[2][2][4][2], const Unit& u, int wr, int wc, int fr, int fq) const {
;         const int trow = u.pm * BM; const bool isc = trow >= 16384; const int ridx = isc ? 4 : (trow >> 12);
;         const float* g = gate + (size_t)ridx * 12288; const int row0 = (isc ? trow - 16384 : trow) + wr * 64 + fr; const int col0 = u.pn * BM + wc * 32 + 8 * fq;
; #pragma unroll
;         for (int bj = 0; bj < 2; ++bj) { const f32x4 g0 = *(const f32x4*)(g + col0 + bj * HALF), g1 = *(const f32x4*)(g + col0 + bj * HALF + 4);
; #pragma unroll
;             for (int ai = 0; ai < 2; ++ai)
; #pragma unroll
;                 for (int m = 0; m < 4; ++m) { const size_t off = (size_t)(row0 + ai * HALF + m * 16) * 2048 + col0 + bj * HALF;
;                     if (isc) { *(f32x4*)(outC + off) = *(const f32x4*)(baseC + off) + g0 * acc[ai][bj][m][0]; *(f32x4*)(outC + off + 4) = *(const f32x4*)(baseC + off + 4) + g1 * acc[ai][bj][m][1]; }
;                     else { f32x4 b0, b1;
;                         if (BASE_BF16) { const u32x4 w = *(const u32x4*)(baseLb + off);
;                             b0 = (f32x4){__uint_as_float(w.x << 16), __uint_as_float(w.x & 0xffff0000u), __uint_as_float(w.y << 16), __uint_as_float(w.y & 0xffff0000u)};
;                             b1 = (f32x4){__uint_as_float(w.z << 16), __uint_as_float(w.z & 0xffff0000u), __uint_as_float(w.w << 16), __uint_as_float(w.w & 0xffff0000u)}; }
;                         else { b0 = *(const f32x4*)(baseLf + off); b1 = *(const f32x4*)(baseLf + off + 4); }
;                         const f32x4 o0 = b0 + g0 * acc[ai][bj][m][0], o1 = b1 + g1 * acc[ai][bj][m][1];
;                         u32x4 w; w.x = cvt_pk_bf16(o0[0], o0[1]); w.y = cvt_pk_bf16(o0[2], o0[3]); w.z = cvt_pk_bf16(o1[0], o1[1]); w.w = cvt_pk_bf16(o1[2], o1[3]);
;                         *(u32x4*)(outLb + off) = w; } } }
.LBB0_1330:
	s_lshl_b32 s20, s16, 8
	s_cmp_lt_i32 s16, 64
	s_cselect_b64 s[8:9], -1, 0
	s_min_i32 s10, s16, 64
	s_ashr_i32 s10, s10, 4
	s_mul_hi_i32 s11, s10, 0xc000
	s_mul_i32 s10, s10, 0xc000
	s_add_u32 s10, s22, s10
	v_lshl_or_b32 v152, s18, 8, v164
	s_addc_u32 s11, s23, s11
	v_ashrrev_i32_e32 v153, 31, v152
	v_lshl_add_u64 v[154:155], v[152:153], 2, s[10:11]
	global_load_dwordx4 v[112:115], v[154:155], off offset:16
	global_load_dwordx4 v[120:123], v[154:155], off
	s_add_i32 s10, s20, 0xffffc000
	s_cmp_gt_i32 s16, 63
	s_cselect_b32 s10, s10, s20
	v_add_u32_e32 v158, s10, v162
	v_ashrrev_i32_e32 v159, 31, v158
	v_lshlrev_b64 v[156:157], 11, v[158:159]
	v_lshl_add_u64 v[160:161], v[156:157], 0, v[152:153]
	v_lshl_add_u64 v[252:253], v[160:161], 1, s[4:5]
	s_mov_b64 s[98:99], 0x10000
	s_mov_b64 s[100:101], 0x50000
	global_load_dwordx4 v[182:185], v[252:253], off
	global_load_dwordx4 v[214:217], v[252:253], off offset:256
	v_lshl_add_u64 v[252:253], v[252:253], 0, s[98:99]
	global_load_dwordx4 v[186:189], v[252:253], off
	global_load_dwordx4 v[224:227], v[252:253], off offset:256
	v_lshl_add_u64 v[252:253], v[252:253], 0, s[98:99]
	global_load_dwordx4 v[190:193], v[252:253], off
	global_load_dwordx4 v[228:231], v[252:253], off offset:256
	v_lshl_add_u64 v[252:253], v[252:253], 0, s[98:99]
	global_load_dwordx4 v[194:197], v[252:253], off
	global_load_dwordx4 v[232:235], v[252:253], off offset:256
	v_lshl_add_u64 v[252:253], v[252:253], 0, s[100:101]
	global_load_dwordx4 v[198:201], v[252:253], off
	global_load_dwordx4 v[236:239], v[252:253], off offset:256
	v_lshl_add_u64 v[252:253], v[252:253], 0, s[98:99]
	global_load_dwordx4 v[202:205], v[252:253], off
	global_load_dwordx4 v[240:243], v[252:253], off offset:256
	v_lshl_add_u64 v[252:253], v[252:253], 0, s[98:99]
	global_load_dwordx4 v[206:209], v[252:253], off
	global_load_dwordx4 v[244:247], v[252:253], off offset:256
	v_lshl_add_u64 v[252:253], v[252:253], 0, s[98:99]
	global_load_dwordx4 v[210:213], v[252:253], off
	global_load_dwordx4 v[248:251], v[252:253], off offset:256
	s_mov_b64 s[10:11], -1
	s_and_b64 vcc, exec, s[8:9]
	s_cbranch_vccz .LBB0_1332
	v_lshlrev_b64 v[172:173], 1, v[160:161]
	v_lshl_add_u64 v[168:169], s[4:5], 0, v[172:173]
	s_waitcnt vmcnt(0)
	v_mov_b32_e32 v168, v182
	v_mov_b32_e32 v169, v183
	v_mov_b32_e32 v170, v184
	v_mov_b32_e32 v171, v185
	v_lshl_add_u64 v[172:173], s[14:15], 0, v[172:173]
	s_mov_b64 s[10:11], 0
	v_lshlrev_b32_e32 v174, 16, v168
	v_and_b32_e32 v175, 0xffff0000, v168
	v_lshlrev_b32_e32 v168, 16, v169
	v_and_b32_e32 v169, 0xffff0000, v169
	v_lshlrev_b32_e32 v176, 16, v170
	v_and_b32_e32 v177, 0xffff0000, v170
	v_lshlrev_b32_e32 v170, 16, v171
	v_and_b32_e32 v171, 0xffff0000, v171
	v_pk_fma_f32 v[178:179], v[134:135], v[122:123], v[168:169]
	v_pk_fma_f32 v[168:169], v[132:133], v[120:121], v[174:175]
	v_pk_fma_f32 v[174:175], v[130:131], v[114:115], v[170:171]
	v_pk_fma_f32 v[170:171], v[128:129], v[112:113], v[176:177]
	v_cvt_pk_bf16_f32 v168, v168, v169
	v_cvt_pk_bf16_f32 v169, v178, v179
	s_nop 0
	v_cvt_pk_bf16_f32 v170, v170, v171
	v_cvt_pk_bf16_f32 v171, v174, v175
	global_store_dwordx4 v[172:173], v[168:171], off

; __device__ __forceinline__ unsigned cvt_pk_bf16(float lo, float hi) { unsigned r; asm volatile("v_cvt_pk_bf16_f32 %0, %1, %2" : "=v"(r) : "v"(lo), "v"(hi)); return r; }
;     __device__ __forceinline__ void operator()(const f32x4 (&acc)[2][2][4][2], const Unit& u, int wr, int wc, int fr, int fq) const {
;     ...
;                 for (int m = 0; m < 4; ++m) { const size_t off = (size_t)(row0 + ai * HALF + m * 16) * 2048 + col0 + bj * HALF;
;                     if (isc) { *(f32x4*)(outC + off) = *(const f32x4*)(baseC + off) + g0 * acc[ai][bj][m][0]; *(f32x4*)(outC + off + 4) = *(const f32x4*)(baseC + off + 4) + g1 * acc[ai][bj][m][1]; }
;                     else { f32x4 b0, b1;
;                         if (BASE_BF16) { const u32x4 w = *(const u32x4*)(baseLb + off);
;                             b0 = (f32x4){__uint_as_float(w.x << 16), __uint_as_float(w.x & 0xffff0000u), __uint_as_float(w.y << 16), __uint_as_float(w.y & 0xffff0000u)};
;                             b1 = (f32x4){__uint_as_float(w.z << 16), __uint_as_float(w.z & 0xffff0000u), __uint_as_float(w.w << 16), __uint_as_float(w.w & 0xffff0000u)}; }
;                         else { b0 = *(const f32x4*)(baseLf + off); b1 = *(const f32x4*)(baseLf + off + 4); }
;                         const f32x4 o0 = b0 + g0 * acc[ai][bj][m][0], o1 = b1 + g1 * acc[ai][bj][m][1];
;                         u32x4 w; w.x = cvt_pk_bf16(o0[0], o0[1]); w.y = cvt_pk_bf16(o0[2], o0[3]); w.z = cvt_pk_bf16(o1[0], o1[1]); w.w = cvt_pk_bf16(o1[2], o1[3]);
;                         *(u32x4*)(outLb + off) = w; } } }
.LBB0_1334:
	s_nop 1
	v_or_b32_e32 v128, 16, v158
	v_ashrrev_i32_e32 v129, 31, v128
	v_lshlrev_b64 v[128:129], 11, v[128:129]
	v_cndmask_b32_e64 v132, 0, 1, s[8:9]
	v_lshl_add_u64 v[130:131], v[128:129], 0, v[152:153]
	v_cmp_ne_u32_e64 s[40:41], 1, v132
	s_andn2_b64 vcc, exec, s[8:9]
	s_mov_b64 s[8:9], -1
	s_cbranch_vccnz .LBB0_1336
	v_lshlrev_b64 v[160:161], 1, v[130:131]
	v_lshl_add_u64 v[132:133], s[4:5], 0, v[160:161]
	v_mov_b32_e32 v132, v186
	v_mov_b32_e32 v133, v187
	v_mov_b32_e32 v134, v188
	v_mov_b32_e32 v135, v189
	v_lshl_add_u64 v[160:161], s[14:15], 0, v[160:161]
	s_mov_b64 s[8:9], 0
	v_lshlrev_b32_e32 v168, 16, v132
	v_and_b32_e32 v169, 0xffff0000, v132
	v_lshlrev_b32_e32 v132, 16, v133
	v_and_b32_e32 v133, 0xffff0000, v133
	v_lshlrev_b32_e32 v170, 16, v134
	v_and_b32_e32 v171, 0xffff0000, v134
	v_lshlrev_b32_e32 v134, 16, v135
	v_and_b32_e32 v135, 0xffff0000, v135
	v_pk_fma_f32 v[172:173], v[126:127], v[122:123], v[132:133]
	v_pk_fma_f32 v[132:133], v[124:125], v[120:121], v[168:169]
	v_pk_fma_f32 v[168:169], v[118:119], v[114:115], v[134:135]
	v_pk_fma_f32 v[134:135], v[116:117], v[112:113], v[170:171]
	v_cvt_pk_bf16_f32 v132, v132, v133
	v_cvt_pk_bf16_f32 v133, v172, v173
	s_nop 0
	v_cvt_pk_bf16_f32 v134, v134, v135
	v_cvt_pk_bf16_f32 v135, v168, v169
	global_store_dwordx4 v[160:161], v[132:135], off

; __device__ __forceinline__ unsigned cvt_pk_bf16(float lo, float hi) { unsigned r; asm volatile("v_cvt_pk_bf16_f32 %0, %1, %2" : "=v"(r) : "v"(lo), "v"(hi)); return r; }
;     __device__ __forceinline__ void operator()(const f32x4 (&acc)[2][2][4][2], const Unit& u, int wr, int wc, int fr, int fq) const {
;     ...
;                 for (int m = 0; m < 4; ++m) { const size_t off = (size_t)(row0 + ai * HALF + m * 16) * 2048 + col0 + bj * HALF;
;                     if (isc) { *(f32x4*)(outC + off) = *(const f32x4*)(baseC + off) + g0 * acc[ai][bj][m][0]; *(f32x4*)(outC + off + 4) = *(const f32x4*)(baseC + off + 4) + g1 * acc[ai][bj][m][1]; }
;                     else { f32x4 b0, b1;
;                         if (BASE_BF16) { const u32x4 w = *(const u32x4*)(baseLb + off);
;                             b0 = (f32x4){__uint_as_float(w.x << 16), __uint_as_float(w.x & 0xffff0000u), __uint_as_float(w.y << 16), __uint_as_float(w.y & 0xffff0000u)};
;                             b1 = (f32x4){__uint_as_float(w.z << 16), __uint_as_float(w.z & 0xffff0000u), __uint_as_float(w.w << 16), __uint_as_float(w.w & 0xffff0000u)}; }
;                         else { b0 = *(const f32x4*)(baseLf + off); b1 = *(const f32x4*)(baseLf + off + 4); }
;                         const f32x4 o0 = b0 + g0 * acc[ai][bj][m][0], o1 = b1 + g1 * acc[ai][bj][m][1];
;                         u32x4 w; w.x = cvt_pk_bf16(o0[0], o0[1]); w.y = cvt_pk_bf16(o0[2], o0[3]); w.z = cvt_pk_bf16(o1[0], o1[1]); w.w = cvt_pk_bf16(o1[2], o1[3]);
;                         *(u32x4*)(outLb + off) = w; } } }
.LBB0_1338:
	s_nop 1
	v_or_b32_e32 v116, 32, v158
	v_ashrrev_i32_e32 v117, 31, v116
	v_lshlrev_b64 v[116:117], 11, v[116:117]
	v_lshl_add_u64 v[118:119], v[116:117], 0, v[152:153]
	s_and_b64 vcc, exec, s[40:41]
	s_mov_b64 s[8:9], -1
	s_cbranch_vccnz .LBB0_1340
	v_lshlrev_b64 v[130:131], 1, v[118:119]
	v_lshl_add_u64 v[124:125], s[4:5], 0, v[130:131]
	v_mov_b32_e32 v124, v190
	v_mov_b32_e32 v125, v191
	v_mov_b32_e32 v126, v192
	v_mov_b32_e32 v127, v193
	v_lshl_add_u64 v[130:131], s[14:15], 0, v[130:131]
	s_mov_b64 s[8:9], 0
	v_lshlrev_b32_e32 v132, 16, v124
	v_and_b32_e32 v133, 0xffff0000, v124
	v_lshlrev_b32_e32 v124, 16, v125
	v_and_b32_e32 v125, 0xffff0000, v125
	v_lshlrev_b32_e32 v134, 16, v126
	v_and_b32_e32 v135, 0xffff0000, v126
	v_lshlrev_b32_e32 v126, 16, v127
	v_and_b32_e32 v127, 0xffff0000, v127
	v_pk_fma_f32 v[160:161], v[110:111], v[122:123], v[124:125]
	v_pk_fma_f32 v[124:125], v[108:109], v[120:121], v[132:133]
	v_pk_fma_f32 v[132:133], v[106:107], v[114:115], v[126:127]
	v_pk_fma_f32 v[126:127], v[104:105], v[112:113], v[134:135]
	v_cvt_pk_bf16_f32 v124, v124, v125
	v_cvt_pk_bf16_f32 v125, v160, v161
	s_nop 0
	v_cvt_pk_bf16_f32 v126, v126, v127
	v_cvt_pk_bf16_f32 v127, v132, v133
	global_store_dwordx4 v[130:131], v[124:127], off

; __device__ __forceinline__ unsigned cvt_pk_bf16(float lo, float hi) { unsigned r; asm volatile("v_cvt_pk_bf16_f32 %0, %1, %2" : "=v"(r) : "v"(lo), "v"(hi)); return r; }
;     __device__ __forceinline__ void operator()(const f32x4 (&acc)[2][2][4][2], const Unit& u, int wr, int wc, int fr, int fq) const {
;     ...
;                 for (int m = 0; m < 4; ++m) { const size_t off = (size_t)(row0 + ai * HALF + m * 16) * 2048 + col0 + bj * HALF;
;                     if (isc) { *(f32x4*)(outC + off) = *(const f32x4*)(baseC + off) + g0 * acc[ai][bj][m][0]; *(f32x4*)(outC + off + 4) = *(const f32x4*)(baseC + off + 4) + g1 * acc[ai][bj][m][1]; }
;                     else { f32x4 b0, b1;
;                         if (BASE_BF16) { const u32x4 w = *(const u32x4*)(baseLb + off);
;                             b0 = (f32x4){__uint_as_float(w.x << 16), __uint_as_float(w.x & 0xffff0000u), __uint_as_float(w.y << 16), __uint_as_float(w.y & 0xffff0000u)};
;                             b1 = (f32x4){__uint_as_float(w.z << 16), __uint_as_float(w.z & 0xffff0000u), __uint_as_float(w.w << 16), __uint_as_float(w.w & 0xffff0000u)}; }
;                         else { b0 = *(const f32x4*)(baseLf + off); b1 = *(const f32x4*)(baseLf + off + 4); }
;                         const f32x4 o0 = b0 + g0 * acc[ai][bj][m][0], o1 = b1 + g1 * acc[ai][bj][m][1];
;                         u32x4 w; w.x = cvt_pk_bf16(o0[0], o0[1]); w.y = cvt_pk_bf16(o0[2], o0[3]); w.z = cvt_pk_bf16(o1[0], o1[1]); w.w = cvt_pk_bf16(o1[2], o1[3]);
;                         *(u32x4*)(outLb + off) = w; } } }
.LBB0_1342:
	s_nop 1
	v_or_b32_e32 v104, 48, v158
	v_ashrrev_i32_e32 v105, 31, v104
	v_lshlrev_b64 v[104:105], 11, v[104:105]
	v_lshl_add_u64 v[106:107], v[104:105], 0, v[152:153]
	s_and_b64 vcc, exec, s[40:41]
	s_mov_b64 s[8:9], -1
	s_cbranch_vccnz .LBB0_1344
	v_lshlrev_b64 v[118:119], 1, v[106:107]
	v_lshl_add_u64 v[108:109], s[4:5], 0, v[118:119]
	v_mov_b32_e32 v108, v194
	v_mov_b32_e32 v109, v195
	v_mov_b32_e32 v110, v196
	v_mov_b32_e32 v111, v197
	v_lshl_add_u64 v[118:119], s[14:15], 0, v[118:119]
	s_mov_b64 s[8:9], 0
	v_lshlrev_b32_e32 v124, 16, v108
	v_and_b32_e32 v125, 0xffff0000, v108
	v_lshlrev_b32_e32 v108, 16, v109
	v_and_b32_e32 v109, 0xffff0000, v109
	v_lshlrev_b32_e32 v126, 16, v110
	v_and_b32_e32 v127, 0xffff0000, v110
	v_lshlrev_b32_e32 v110, 16, v111
	v_and_b32_e32 v111, 0xffff0000, v111
	v_pk_fma_f32 v[130:131], v[102:103], v[122:123], v[108:109]
	v_pk_fma_f32 v[108:109], v[100:101], v[120:121], v[124:125]
	v_pk_fma_f32 v[124:125], v[98:99], v[114:115], v[110:111]
	v_pk_fma_f32 v[110:111], v[96:97], v[112:113], v[126:127]
	v_cvt_pk_bf16_f32 v108, v108, v109
	v_cvt_pk_bf16_f32 v109, v130, v131
	s_nop 0
	v_cvt_pk_bf16_f32 v110, v110, v111
	v_cvt_pk_bf16_f32 v111, v124, v125
	global_store_dwordx4 v[118:119], v[108:111], off

; __device__ __forceinline__ unsigned cvt_pk_bf16(float lo, float hi) { unsigned r; asm volatile("v_cvt_pk_bf16_f32 %0, %1, %2" : "=v"(r) : "v"(lo), "v"(hi)); return r; }
;     __device__ __forceinline__ void operator()(const f32x4 (&acc)[2][2][4][2], const Unit& u, int wr, int wc, int fr, int fq) const {
;     ...
;                 for (int m = 0; m < 4; ++m) { const size_t off = (size_t)(row0 + ai * HALF + m * 16) * 2048 + col0 + bj * HALF;
;                     if (isc) { *(f32x4*)(outC + off) = *(const f32x4*)(baseC + off) + g0 * acc[ai][bj][m][0]; *(f32x4*)(outC + off + 4) = *(const f32x4*)(baseC + off + 4) + g1 * acc[ai][bj][m][1]; }
;                     else { f32x4 b0, b1;
;                         if (BASE_BF16) { const u32x4 w = *(const u32x4*)(baseLb + off);
;                             b0 = (f32x4){__uint_as_float(w.x << 16), __uint_as_float(w.x & 0xffff0000u), __uint_as_float(w.y << 16), __uint_as_float(w.y & 0xffff0000u)};
;                             b1 = (f32x4){__uint_as_float(w.z << 16), __uint_as_float(w.z & 0xffff0000u), __uint_as_float(w.w << 16), __uint_as_float(w.w & 0xffff0000u)}; }
;                         else { b0 = *(const f32x4*)(baseLf + off); b1 = *(const f32x4*)(baseLf + off + 4); }
;                         const f32x4 o0 = b0 + g0 * acc[ai][bj][m][0], o1 = b1 + g1 * acc[ai][bj][m][1];
;                         u32x4 w; w.x = cvt_pk_bf16(o0[0], o0[1]); w.y = cvt_pk_bf16(o0[2], o0[3]); w.z = cvt_pk_bf16(o1[0], o1[1]); w.w = cvt_pk_bf16(o1[2], o1[3]);
;                         *(u32x4*)(outLb + off) = w; } } }
.LBB0_1346:
	s_nop 1
	v_lshlrev_b64 v[96:97], 11, v[158:159]
	s_mov_b64 s[8:9], 0x40000
	v_lshl_add_u64 v[96:97], v[96:97], 0, s[8:9]
	v_lshl_add_u64 v[98:99], v[96:97], 0, v[152:153]
	s_and_b64 vcc, exec, s[40:41]
	s_mov_b64 s[8:9], -1
	s_cbranch_vccnz .LBB0_1348
	v_lshlrev_b64 v[106:107], 1, v[98:99]
	v_lshl_add_u64 v[100:101], s[4:5], 0, v[106:107]
	v_mov_b32_e32 v100, v198
	v_mov_b32_e32 v101, v199
	v_mov_b32_e32 v102, v200
	v_mov_b32_e32 v103, v201
	v_lshl_add_u64 v[106:107], s[14:15], 0, v[106:107]
	s_mov_b64 s[8:9], 0
	v_lshlrev_b32_e32 v108, 16, v100
	v_and_b32_e32 v109, 0xffff0000, v100
	v_lshlrev_b32_e32 v100, 16, v101
	v_and_b32_e32 v101, 0xffff0000, v101
	v_lshlrev_b32_e32 v110, 16, v102
	v_and_b32_e32 v111, 0xffff0000, v102
	v_lshlrev_b32_e32 v102, 16, v103
	v_and_b32_e32 v103, 0xffff0000, v103
	v_pk_fma_f32 v[118:119], v[94:95], v[122:123], v[100:101]
	v_pk_fma_f32 v[100:101], v[92:93], v[120:121], v[108:109]
	v_pk_fma_f32 v[108:109], v[90:91], v[114:115], v[102:103]
	v_pk_fma_f32 v[102:103], v[88:89], v[112:113], v[110:111]
	v_cvt_pk_bf16_f32 v100, v100, v101
	v_cvt_pk_bf16_f32 v101, v118, v119
	s_nop 0
	v_cvt_pk_bf16_f32 v102, v102, v103
	v_cvt_pk_bf16_f32 v103, v108, v109
	global_store_dwordx4 v[106:107], v[100:103], off

; __device__ __forceinline__ unsigned cvt_pk_bf16(float lo, float hi) { unsigned r; asm volatile("v_cvt_pk_bf16_f32 %0, %1, %2" : "=v"(r) : "v"(lo), "v"(hi)); return r; }
;     __device__ __forceinline__ void operator()(const f32x4 (&acc)[2][2][4][2], const Unit& u, int wr, int wc, int fr, int fq) const {
;     ...
;                 for (int m = 0; m < 4; ++m) { const size_t off = (size_t)(row0 + ai * HALF + m * 16) * 2048 + col0 + bj * HALF;
;                     if (isc) { *(f32x4*)(outC + off) = *(const f32x4*)(baseC + off) + g0 * acc[ai][bj][m][0]; *(f32x4*)(outC + off + 4) = *(const f32x4*)(baseC + off + 4) + g1 * acc[ai][bj][m][1]; }
;                     else { f32x4 b0, b1;
;                         if (BASE_BF16) { const u32x4 w = *(const u32x4*)(baseLb + off);
;                             b0 = (f32x4){__uint_as_float(w.x << 16), __uint_as_float(w.x & 0xffff0000u), __uint_as_float(w.y << 16), __uint_as_float(w.y & 0xffff0000u)};
;                             b1 = (f32x4){__uint_as_float(w.z << 16), __uint_as_float(w.z & 0xffff0000u), __uint_as_float(w.w << 16), __uint_as_float(w.w & 0xffff0000u)}; }
;                         else { b0 = *(const f32x4*)(baseLf + off); b1 = *(const f32x4*)(baseLf + off + 4); }
;                         const f32x4 o0 = b0 + g0 * acc[ai][bj][m][0], o1 = b1 + g1 * acc[ai][bj][m][1];
;                         u32x4 w; w.x = cvt_pk_bf16(o0[0], o0[1]); w.y = cvt_pk_bf16(o0[2], o0[3]); w.z = cvt_pk_bf16(o1[0], o1[1]); w.w = cvt_pk_bf16(o1[2], o1[3]);
;                         *(u32x4*)(outLb + off) = w; } } }
.LBB0_1350:
	s_nop 1
	v_lshlrev_b64 v[88:89], 11, v[158:159]
	s_mov_b64 s[8:9], 0x48000
	v_lshl_add_u64 v[88:89], v[88:89], 0, s[8:9]
	v_lshl_add_u64 v[90:91], v[88:89], 0, v[152:153]
	s_and_b64 vcc, exec, s[40:41]
	s_mov_b64 s[8:9], -1
	s_cbranch_vccnz .LBB0_1352
	v_lshlrev_b64 v[98:99], 1, v[90:91]
	v_lshl_add_u64 v[92:93], s[4:5], 0, v[98:99]
	v_mov_b32_e32 v92, v202
	v_mov_b32_e32 v93, v203
	v_mov_b32_e32 v94, v204
	v_mov_b32_e32 v95, v205
	v_lshl_add_u64 v[98:99], s[14:15], 0, v[98:99]
	s_mov_b64 s[8:9], 0
	v_lshlrev_b32_e32 v100, 16, v92
	v_and_b32_e32 v101, 0xffff0000, v92
	v_lshlrev_b32_e32 v92, 16, v93
	v_and_b32_e32 v93, 0xffff0000, v93
	v_lshlrev_b32_e32 v102, 16, v94
	v_and_b32_e32 v103, 0xffff0000, v94
	v_lshlrev_b32_e32 v94, 16, v95
	v_and_b32_e32 v95, 0xffff0000, v95
	v_pk_fma_f32 v[106:107], v[86:87], v[122:123], v[92:93]
	v_pk_fma_f32 v[92:93], v[84:85], v[120:121], v[100:101]
	v_pk_fma_f32 v[100:101], v[82:83], v[114:115], v[94:95]
	v_pk_fma_f32 v[94:95], v[80:81], v[112:113], v[102:103]
	v_cvt_pk_bf16_f32 v92, v92, v93
	v_cvt_pk_bf16_f32 v93, v106, v107
	s_nop 0
	v_cvt_pk_bf16_f32 v94, v94, v95
	v_cvt_pk_bf16_f32 v95, v100, v101
	global_store_dwordx4 v[98:99], v[92:95], off

; __device__ __forceinline__ unsigned cvt_pk_bf16(float lo, float hi) { unsigned r; asm volatile("v_cvt_pk_bf16_f32 %0, %1, %2" : "=v"(r) : "v"(lo), "v"(hi)); return r; }
;     __device__ __forceinline__ void operator()(const f32x4 (&acc)[2][2][4][2], const Unit& u, int wr, int wc, int fr, int fq) const {
;     ...
;                 for (int m = 0; m < 4; ++m) { const size_t off = (size_t)(row0 + ai * HALF + m * 16) * 2048 + col0 + bj * HALF;
;                     if (isc) { *(f32x4*)(outC + off) = *(const f32x4*)(baseC + off) + g0 * acc[ai][bj][m][0]; *(f32x4*)(outC + off + 4) = *(const f32x4*)(baseC + off + 4) + g1 * acc[ai][bj][m][1]; }
;                     else { f32x4 b0, b1;
;                         if (BASE_BF16) { const u32x4 w = *(const u32x4*)(baseLb + off);
;                             b0 = (f32x4){__uint_as_float(w.x << 16), __uint_as_float(w.x & 0xffff0000u), __uint_as_float(w.y << 16), __uint_as_float(w.y & 0xffff0000u)};
;                             b1 = (f32x4){__uint_as_float(w.z << 16), __uint_as_float(w.z & 0xffff0000u), __uint_as_float(w.w << 16), __uint_as_float(w.w & 0xffff0000u)}; }
;                         else { b0 = *(const f32x4*)(baseLf + off); b1 = *(const f32x4*)(baseLf + off + 4); }
;                         const f32x4 o0 = b0 + g0 * acc[ai][bj][m][0], o1 = b1 + g1 * acc[ai][bj][m][1];
;                         u32x4 w; w.x = cvt_pk_bf16(o0[0], o0[1]); w.y = cvt_pk_bf16(o0[2], o0[3]); w.z = cvt_pk_bf16(o1[0], o1[1]); w.w = cvt_pk_bf16(o1[2], o1[3]);
;                         *(u32x4*)(outLb + off) = w; } } }
.LBB0_1354:
	s_nop 1
	v_lshlrev_b64 v[80:81], 11, v[158:159]
	s_mov_b64 s[8:9], 0x50000
	v_lshl_add_u64 v[80:81], v[80:81], 0, s[8:9]
	v_lshl_add_u64 v[82:83], v[80:81], 0, v[152:153]
	s_and_b64 vcc, exec, s[40:41]
	s_mov_b64 s[8:9], -1
	s_cbranch_vccnz .LBB0_1356
	v_lshlrev_b64 v[90:91], 1, v[82:83]
	v_lshl_add_u64 v[84:85], s[4:5], 0, v[90:91]
	v_mov_b32_e32 v84, v206
	v_mov_b32_e32 v85, v207
	v_mov_b32_e32 v86, v208
	v_mov_b32_e32 v87, v209
	v_lshl_add_u64 v[90:91], s[14:15], 0, v[90:91]
	s_mov_b64 s[8:9], 0
	v_lshlrev_b32_e32 v92, 16, v84
	v_and_b32_e32 v93, 0xffff0000, v84
	v_lshlrev_b32_e32 v84, 16, v85
	v_and_b32_e32 v85, 0xffff0000, v85
	v_lshlrev_b32_e32 v94, 16, v86
	v_and_b32_e32 v95, 0xffff0000, v86
	v_lshlrev_b32_e32 v86, 16, v87
	v_and_b32_e32 v87, 0xffff0000, v87
	v_pk_fma_f32 v[98:99], v[78:79], v[122:123], v[84:85]
	v_pk_fma_f32 v[84:85], v[76:77], v[120:121], v[92:93]
	v_pk_fma_f32 v[92:93], v[74:75], v[114:115], v[86:87]
	v_pk_fma_f32 v[86:87], v[72:73], v[112:113], v[94:95]
	v_cvt_pk_bf16_f32 v84, v84, v85
	v_cvt_pk_bf16_f32 v85, v98, v99
	s_nop 0
	v_cvt_pk_bf16_f32 v86, v86, v87
	v_cvt_pk_bf16_f32 v87, v92, v93
	global_store_dwordx4 v[90:91], v[84:87], off

; __device__ __forceinline__ unsigned cvt_pk_bf16(float lo, float hi) { unsigned r; asm volatile("v_cvt_pk_bf16_f32 %0, %1, %2" : "=v"(r) : "v"(lo), "v"(hi)); return r; }
;     __device__ __forceinline__ void operator()(const f32x4 (&acc)[2][2][4][2], const Unit& u, int wr, int wc, int fr, int fq) const {
;     ...
;                 for (int m = 0; m < 4; ++m) { const size_t off = (size_t)(row0 + ai * HALF + m * 16) * 2048 + col0 + bj * HALF;
;                     if (isc) { *(f32x4*)(outC + off) = *(const f32x4*)(baseC + off) + g0 * acc[ai][bj][m][0]; *(f32x4*)(outC + off + 4) = *(const f32x4*)(baseC + off + 4) + g1 * acc[ai][bj][m][1]; }
;                     else { f32x4 b0, b1;
;                         if (BASE_BF16) { const u32x4 w = *(const u32x4*)(baseLb + off);
;                             b0 = (f32x4){__uint_as_float(w.x << 16), __uint_as_float(w.x & 0xffff0000u), __uint_as_float(w.y << 16), __uint_as_float(w.y & 0xffff0000u)};
;                             b1 = (f32x4){__uint_as_float(w.z << 16), __uint_as_float(w.z & 0xffff0000u), __uint_as_float(w.w << 16), __uint_as_float(w.w & 0xffff0000u)}; }
;                         else { b0 = *(const f32x4*)(baseLf + off); b1 = *(const f32x4*)(baseLf + off + 4); }
;                         const f32x4 o0 = b0 + g0 * acc[ai][bj][m][0], o1 = b1 + g1 * acc[ai][bj][m][1];
;                         u32x4 w; w.x = cvt_pk_bf16(o0[0], o0[1]); w.y = cvt_pk_bf16(o0[2], o0[3]); w.z = cvt_pk_bf16(o1[0], o1[1]); w.w = cvt_pk_bf16(o1[2], o1[3]);
;                         *(u32x4*)(outLb + off) = w; } } }
.LBB0_1358:
	s_nop 1
	v_lshlrev_b64 v[72:73], 11, v[158:159]
	s_mov_b64 s[8:9], 0x58000
	v_lshl_add_u64 v[72:73], v[72:73], 0, s[8:9]
	v_lshl_add_u64 v[74:75], v[72:73], 0, v[152:153]
	s_and_b64 vcc, exec, s[40:41]
	s_mov_b64 s[8:9], -1
	s_cbranch_vccnz .LBB0_1360
	v_lshlrev_b64 v[82:83], 1, v[74:75]
	v_lshl_add_u64 v[76:77], s[4:5], 0, v[82:83]
	v_mov_b32_e32 v76, v210
	v_mov_b32_e32 v77, v211
	v_mov_b32_e32 v78, v212
	v_mov_b32_e32 v79, v213
	v_lshl_add_u64 v[82:83], s[14:15], 0, v[82:83]
	s_mov_b64 s[8:9], 0
	v_lshlrev_b32_e32 v84, 16, v76
	v_and_b32_e32 v85, 0xffff0000, v76
	v_lshlrev_b32_e32 v76, 16, v77
	v_and_b32_e32 v77, 0xffff0000, v77
	v_lshlrev_b32_e32 v86, 16, v78
	v_and_b32_e32 v87, 0xffff0000, v78
	v_lshlrev_b32_e32 v78, 16, v79
	v_and_b32_e32 v79, 0xffff0000, v79
	v_pk_fma_f32 v[90:91], v[70:71], v[122:123], v[76:77]
	v_pk_fma_f32 v[76:77], v[68:69], v[120:121], v[84:85]
	v_pk_fma_f32 v[84:85], v[66:67], v[114:115], v[78:79]
	v_pk_fma_f32 v[78:79], v[64:65], v[112:113], v[86:87]
	v_cvt_pk_bf16_f32 v76, v76, v77
	v_cvt_pk_bf16_f32 v77, v90, v91
	s_nop 0
	v_cvt_pk_bf16_f32 v78, v78, v79
	v_cvt_pk_bf16_f32 v79, v84, v85
	global_store_dwordx4 v[82:83], v[76:79], off

; __device__ __forceinline__ unsigned cvt_pk_bf16(float lo, float hi) { unsigned r; asm volatile("v_cvt_pk_bf16_f32 %0, %1, %2" : "=v"(r) : "v"(lo), "v"(hi)); return r; }
;     __device__ __forceinline__ void operator()(const f32x4 (&acc)[2][2][4][2], const Unit& u, int wr, int wc, int fr, int fq) const {
;     ...
;         for (int bj = 0; bj < 2; ++bj) { const f32x4 g0 = *(const f32x4*)(g + col0 + bj * HALF), g1 = *(const f32x4*)(g + col0 + bj * HALF + 4);
; #pragma unroll
;             for (int ai = 0; ai < 2; ++ai)
; #pragma unroll
;                 for (int m = 0; m < 4; ++m) { const size_t off = (size_t)(row0 + ai * HALF + m * 16) * 2048 + col0 + bj * HALF;
;                     if (isc) { *(f32x4*)(outC + off) = *(const f32x4*)(baseC + off) + g0 * acc[ai][bj][m][0]; *(f32x4*)(outC + off + 4) = *(const f32x4*)(baseC + off + 4) + g1 * acc[ai][bj][m][1]; }
;                     else { f32x4 b0, b1;
;                         if (BASE_BF16) { const u32x4 w = *(const u32x4*)(baseLb + off);
;                             b0 = (f32x4){__uint_as_float(w.x << 16), __uint_as_float(w.x & 0xffff0000u), __uint_as_float(w.y << 16), __uint_as_float(w.y & 0xffff0000u)};
;                             b1 = (f32x4){__uint_as_float(w.z << 16), __uint_as_float(w.z & 0xffff0000u), __uint_as_float(w.w << 16), __uint_as_float(w.w & 0xffff0000u)}; }
;                         else { b0 = *(const f32x4*)(baseLf + off); b1 = *(const f32x4*)(baseLf + off + 4); }
;                         const f32x4 o0 = b0 + g0 * acc[ai][bj][m][0], o1 = b1 + g1 * acc[ai][bj][m][1];
;                         u32x4 w; w.x = cvt_pk_bf16(o0[0], o0[1]); w.y = cvt_pk_bf16(o0[2], o0[3]); w.z = cvt_pk_bf16(o1[0], o1[1]); w.w = cvt_pk_bf16(o1[2], o1[3]);
;                         *(u32x4*)(outLb + off) = w; } } }
.LBB0_1362:
	global_load_dwordx4 v[64:67], v[154:155], off offset:528
	s_nop 0
	global_load_dwordx4 v[68:71], v[154:155], off offset:512
	v_or_b32_e32 v152, 0x80, v152
	v_lshl_add_u64 v[74:75], v[156:157], 0, v[152:153]
	s_and_b64 vcc, exec, s[40:41]
	s_mov_b64 s[8:9], -1
	s_cbranch_vccnz .LBB0_1379
	v_lshlrev_b64 v[82:83], 1, v[74:75]
	v_lshl_add_u64 v[76:77], s[4:5], 0, v[82:83]
	s_waitcnt vmcnt(0)
	v_mov_b32_e32 v76, v214
	v_mov_b32_e32 v77, v215
	v_mov_b32_e32 v78, v216
	v_mov_b32_e32 v79, v217
	v_lshl_add_u64 v[82:83], s[14:15], 0, v[82:83]
	v_lshlrev_b32_e32 v84, 16, v76
	v_and_b32_e32 v85, 0xffff0000, v76
	v_lshlrev_b32_e32 v76, 16, v77
	v_and_b32_e32 v77, 0xffff0000, v77
	v_lshlrev_b32_e32 v86, 16, v78
	v_and_b32_e32 v87, 0xffff0000, v78
	v_lshlrev_b32_e32 v78, 16, v79
	v_and_b32_e32 v79, 0xffff0000, v79
	v_pk_fma_f32 v[90:91], v[62:63], v[70:71], v[76:77]
	v_pk_fma_f32 v[76:77], v[60:61], v[68:69], v[84:85]
	v_pk_fma_f32 v[84:85], v[58:59], v[66:67], v[78:79]
	v_pk_fma_f32 v[78:79], v[56:57], v[64:65], v[86:87]
	v_cvt_pk_bf16_f32 v76, v76, v77
	v_cvt_pk_bf16_f32 v77, v90, v91
	s_nop 0
	v_cvt_pk_bf16_f32 v78, v78, v79
	v_cvt_pk_bf16_f32 v79, v84, v85
	global_store_dwordx4 v[82:83], v[76:79], off
	s_cbranch_execz .LBB0_1380

; __device__ __forceinline__ unsigned cvt_pk_bf16(float lo, float hi) { unsigned r; asm volatile("v_cvt_pk_bf16_f32 %0, %1, %2" : "=v"(r) : "v"(lo), "v"(hi)); return r; }
;     __device__ __forceinline__ void operator()(const f32x4 (&acc)[2][2][4][2], const Unit& u, int wr, int wc, int fr, int fq) const {
;     ...
;                 for (int m = 0; m < 4; ++m) { const size_t off = (size_t)(row0 + ai * HALF + m * 16) * 2048 + col0 + bj * HALF;
;                     if (isc) { *(f32x4*)(outC + off) = *(const f32x4*)(baseC + off) + g0 * acc[ai][bj][m][0]; *(f32x4*)(outC + off + 4) = *(const f32x4*)(baseC + off + 4) + g1 * acc[ai][bj][m][1]; }
;                     else { f32x4 b0, b1;
;                         if (BASE_BF16) { const u32x4 w = *(const u32x4*)(baseLb + off);
;                             b0 = (f32x4){__uint_as_float(w.x << 16), __uint_as_float(w.x & 0xffff0000u), __uint_as_float(w.y << 16), __uint_as_float(w.y & 0xffff0000u)};
;                             b1 = (f32x4){__uint_as_float(w.z << 16), __uint_as_float(w.z & 0xffff0000u), __uint_as_float(w.w << 16), __uint_as_float(w.w & 0xffff0000u)}; }
;                         else { b0 = *(const f32x4*)(baseLf + off); b1 = *(const f32x4*)(baseLf + off + 4); }
;                         const f32x4 o0 = b0 + g0 * acc[ai][bj][m][0], o1 = b1 + g1 * acc[ai][bj][m][1];
;                         u32x4 w; w.x = cvt_pk_bf16(o0[0], o0[1]); w.y = cvt_pk_bf16(o0[2], o0[3]); w.z = cvt_pk_bf16(o1[0], o1[1]); w.w = cvt_pk_bf16(o1[2], o1[3]);
;                         *(u32x4*)(outLb + off) = w; } } }
.LBB0_1365:
	v_lshlrev_b64 v[62:63], 1, v[56:57]
	v_lshl_add_u64 v[58:59], s[4:5], 0, v[62:63]
	v_mov_b32_e32 v58, v224
	v_mov_b32_e32 v59, v225
	v_mov_b32_e32 v60, v226
	v_mov_b32_e32 v61, v227
	v_lshl_add_u64 v[62:63], s[14:15], 0, v[62:63]
	v_lshlrev_b32_e32 v74, 16, v58
	v_and_b32_e32 v75, 0xffff0000, v58
	v_lshlrev_b32_e32 v58, 16, v59
	v_and_b32_e32 v59, 0xffff0000, v59
	v_lshlrev_b32_e32 v76, 16, v60
	v_and_b32_e32 v77, 0xffff0000, v60
	v_lshlrev_b32_e32 v60, 16, v61
	v_and_b32_e32 v61, 0xffff0000, v61
	v_pk_fma_f32 v[78:79], v[54:55], v[70:71], v[58:59]
	v_pk_fma_f32 v[58:59], v[52:53], v[68:69], v[74:75]
	v_pk_fma_f32 v[74:75], v[50:51], v[66:67], v[60:61]
	v_pk_fma_f32 v[60:61], v[48:49], v[64:65], v[76:77]
	v_cvt_pk_bf16_f32 v58, v58, v59
	v_cvt_pk_bf16_f32 v59, v78, v79
	s_nop 0
	v_cvt_pk_bf16_f32 v60, v60, v61
	v_cvt_pk_bf16_f32 v61, v74, v75
	global_store_dwordx4 v[62:63], v[58:61], off
	s_cbranch_execz .LBB0_1382

; __device__ __forceinline__ unsigned cvt_pk_bf16(float lo, float hi) { unsigned r; asm volatile("v_cvt_pk_bf16_f32 %0, %1, %2" : "=v"(r) : "v"(lo), "v"(hi)); return r; }
;     __device__ __forceinline__ void operator()(const f32x4 (&acc)[2][2][4][2], const Unit& u, int wr, int wc, int fr, int fq) const {
;     ...
;                 for (int m = 0; m < 4; ++m) { const size_t off = (size_t)(row0 + ai * HALF + m * 16) * 2048 + col0 + bj * HALF;
;                     if (isc) { *(f32x4*)(outC + off) = *(const f32x4*)(baseC + off) + g0 * acc[ai][bj][m][0]; *(f32x4*)(outC + off + 4) = *(const f32x4*)(baseC + off + 4) + g1 * acc[ai][bj][m][1]; }
;                     else { f32x4 b0, b1;
;                         if (BASE_BF16) { const u32x4 w = *(const u32x4*)(baseLb + off);
;                             b0 = (f32x4){__uint_as_float(w.x << 16), __uint_as_float(w.x & 0xffff0000u), __uint_as_float(w.y << 16), __uint_as_float(w.y & 0xffff0000u)};
;                             b1 = (f32x4){__uint_as_float(w.z << 16), __uint_as_float(w.z & 0xffff0000u), __uint_as_float(w.w << 16), __uint_as_float(w.w & 0xffff0000u)}; }
;                         else { b0 = *(const f32x4*)(baseLf + off); b1 = *(const f32x4*)(baseLf + off + 4); }
;                         const f32x4 o0 = b0 + g0 * acc[ai][bj][m][0], o1 = b1 + g1 * acc[ai][bj][m][1];
;                         u32x4 w; w.x = cvt_pk_bf16(o0[0], o0[1]); w.y = cvt_pk_bf16(o0[2], o0[3]); w.z = cvt_pk_bf16(o1[0], o1[1]); w.w = cvt_pk_bf16(o1[2], o1[3]);
;                         *(u32x4*)(outLb + off) = w; } } }
.LBB0_1367:
	v_lshlrev_b64 v[54:55], 1, v[48:49]
	v_lshl_add_u64 v[50:51], s[4:5], 0, v[54:55]
	v_mov_b32_e32 v50, v228
	v_mov_b32_e32 v51, v229
	v_mov_b32_e32 v52, v230
	v_mov_b32_e32 v53, v231
	v_lshl_add_u64 v[54:55], s[14:15], 0, v[54:55]
	v_lshlrev_b32_e32 v56, 16, v50
	v_and_b32_e32 v57, 0xffff0000, v50
	v_lshlrev_b32_e32 v50, 16, v51
	v_and_b32_e32 v51, 0xffff0000, v51
	v_lshlrev_b32_e32 v58, 16, v52
	v_and_b32_e32 v59, 0xffff0000, v52
	v_lshlrev_b32_e32 v52, 16, v53
	v_and_b32_e32 v53, 0xffff0000, v53
	v_pk_fma_f32 v[60:61], v[46:47], v[70:71], v[50:51]
	v_pk_fma_f32 v[50:51], v[44:45], v[68:69], v[56:57]
	v_pk_fma_f32 v[56:57], v[42:43], v[66:67], v[52:53]
	v_pk_fma_f32 v[52:53], v[40:41], v[64:65], v[58:59]
	v_cvt_pk_bf16_f32 v50, v50, v51
	v_cvt_pk_bf16_f32 v51, v60, v61
	s_nop 0
	v_cvt_pk_bf16_f32 v52, v52, v53
	v_cvt_pk_bf16_f32 v53, v56, v57
	global_store_dwordx4 v[54:55], v[50:53], off
	s_cbranch_execz .LBB0_1384

; __device__ __forceinline__ unsigned cvt_pk_bf16(float lo, float hi) { unsigned r; asm volatile("v_cvt_pk_bf16_f32 %0, %1, %2" : "=v"(r) : "v"(lo), "v"(hi)); return r; }
;     __device__ __forceinline__ void operator()(const f32x4 (&acc)[2][2][4][2], const Unit& u, int wr, int wc, int fr, int fq) const {
;     ...
;                 for (int m = 0; m < 4; ++m) { const size_t off = (size_t)(row0 + ai * HALF + m * 16) * 2048 + col0 + bj * HALF;
;                     if (isc) { *(f32x4*)(outC + off) = *(const f32x4*)(baseC + off) + g0 * acc[ai][bj][m][0]; *(f32x4*)(outC + off + 4) = *(const f32x4*)(baseC + off + 4) + g1 * acc[ai][bj][m][1]; }
;                     else { f32x4 b0, b1;
;                         if (BASE_BF16) { const u32x4 w = *(const u32x4*)(baseLb + off);
;                             b0 = (f32x4){__uint_as_float(w.x << 16), __uint_as_float(w.x & 0xffff0000u), __uint_as_float(w.y << 16), __uint_as_float(w.y & 0xffff0000u)};
;                             b1 = (f32x4){__uint_as_float(w.z << 16), __uint_as_float(w.z & 0xffff0000u), __uint_as_float(w.w << 16), __uint_as_float(w.w & 0xffff0000u)}; }
;                         else { b0 = *(const f32x4*)(baseLf + off); b1 = *(const f32x4*)(baseLf + off + 4); }
;                         const f32x4 o0 = b0 + g0 * acc[ai][bj][m][0], o1 = b1 + g1 * acc[ai][bj][m][1];
;                         u32x4 w; w.x = cvt_pk_bf16(o0[0], o0[1]); w.y = cvt_pk_bf16(o0[2], o0[3]); w.z = cvt_pk_bf16(o1[0], o1[1]); w.w = cvt_pk_bf16(o1[2], o1[3]);
;                         *(u32x4*)(outLb + off) = w; } } }
.LBB0_1369:
	v_lshlrev_b64 v[46:47], 1, v[40:41]
	v_lshl_add_u64 v[42:43], s[4:5], 0, v[46:47]
	v_mov_b32_e32 v42, v232
	v_mov_b32_e32 v43, v233
	v_mov_b32_e32 v44, v234
	v_mov_b32_e32 v45, v235
	v_lshl_add_u64 v[46:47], s[14:15], 0, v[46:47]
	v_lshlrev_b32_e32 v48, 16, v42
	v_and_b32_e32 v49, 0xffff0000, v42
	v_lshlrev_b32_e32 v42, 16, v43
	v_and_b32_e32 v43, 0xffff0000, v43
	v_lshlrev_b32_e32 v50, 16, v44
	v_and_b32_e32 v51, 0xffff0000, v44
	v_lshlrev_b32_e32 v44, 16, v45
	v_and_b32_e32 v45, 0xffff0000, v45
	v_pk_fma_f32 v[52:53], v[38:39], v[70:71], v[42:43]
	v_pk_fma_f32 v[42:43], v[36:37], v[68:69], v[48:49]
	v_pk_fma_f32 v[48:49], v[34:35], v[66:67], v[44:45]
	v_pk_fma_f32 v[44:45], v[32:33], v[64:65], v[50:51]
	v_cvt_pk_bf16_f32 v42, v42, v43
	v_cvt_pk_bf16_f32 v43, v52, v53
	s_nop 0
	v_cvt_pk_bf16_f32 v44, v44, v45
	v_cvt_pk_bf16_f32 v45, v48, v49
	global_store_dwordx4 v[46:47], v[42:45], off
	s_cbranch_execz .LBB0_1386

; __device__ __forceinline__ unsigned cvt_pk_bf16(float lo, float hi) { unsigned r; asm volatile("v_cvt_pk_bf16_f32 %0, %1, %2" : "=v"(r) : "v"(lo), "v"(hi)); return r; }
;     __device__ __forceinline__ void operator()(const f32x4 (&acc)[2][2][4][2], const Unit& u, int wr, int wc, int fr, int fq) const {
;     ...
;                 for (int m = 0; m < 4; ++m) { const size_t off = (size_t)(row0 + ai * HALF + m * 16) * 2048 + col0 + bj * HALF;
;                     if (isc) { *(f32x4*)(outC + off) = *(const f32x4*)(baseC + off) + g0 * acc[ai][bj][m][0]; *(f32x4*)(outC + off + 4) = *(const f32x4*)(baseC + off + 4) + g1 * acc[ai][bj][m][1]; }
;                     else { f32x4 b0, b1;
;                         if (BASE_BF16) { const u32x4 w = *(const u32x4*)(baseLb + off);
;                             b0 = (f32x4){__uint_as_float(w.x << 16), __uint_as_float(w.x & 0xffff0000u), __uint_as_float(w.y << 16), __uint_as_float(w.y & 0xffff0000u)};
;                             b1 = (f32x4){__uint_as_float(w.z << 16), __uint_as_float(w.z & 0xffff0000u), __uint_as_float(w.w << 16), __uint_as_float(w.w & 0xffff0000u)}; }
;                         else { b0 = *(const f32x4*)(baseLf + off); b1 = *(const f32x4*)(baseLf + off + 4); }
;                         const f32x4 o0 = b0 + g0 * acc[ai][bj][m][0], o1 = b1 + g1 * acc[ai][bj][m][1];
;                         u32x4 w; w.x = cvt_pk_bf16(o0[0], o0[1]); w.y = cvt_pk_bf16(o0[2], o0[3]); w.z = cvt_pk_bf16(o1[0], o1[1]); w.w = cvt_pk_bf16(o1[2], o1[3]);
;                         *(u32x4*)(outLb + off) = w; } } }
.LBB0_1371:
	v_lshlrev_b64 v[38:39], 1, v[32:33]
	v_lshl_add_u64 v[34:35], s[4:5], 0, v[38:39]
	v_mov_b32_e32 v34, v236
	v_mov_b32_e32 v35, v237
	v_mov_b32_e32 v36, v238
	v_mov_b32_e32 v37, v239
	v_lshl_add_u64 v[38:39], s[14:15], 0, v[38:39]
	v_lshlrev_b32_e32 v40, 16, v34
	v_and_b32_e32 v41, 0xffff0000, v34
	v_lshlrev_b32_e32 v34, 16, v35
	v_and_b32_e32 v35, 0xffff0000, v35
	v_lshlrev_b32_e32 v42, 16, v36
	v_and_b32_e32 v43, 0xffff0000, v36
	v_lshlrev_b32_e32 v36, 16, v37
	v_and_b32_e32 v37, 0xffff0000, v37
	v_pk_fma_f32 v[44:45], v[30:31], v[70:71], v[34:35]
	v_pk_fma_f32 v[34:35], v[28:29], v[68:69], v[40:41]
	v_pk_fma_f32 v[40:41], v[26:27], v[66:67], v[36:37]
	v_pk_fma_f32 v[36:37], v[24:25], v[64:65], v[42:43]
	v_cvt_pk_bf16_f32 v34, v34, v35
	v_cvt_pk_bf16_f32 v35, v44, v45
	s_nop 0
	v_cvt_pk_bf16_f32 v36, v36, v37
	v_cvt_pk_bf16_f32 v37, v40, v41
	global_store_dwordx4 v[38:39], v[34:37], off
	s_cbranch_execz .LBB0_1388

; __device__ __forceinline__ unsigned cvt_pk_bf16(float lo, float hi) { unsigned r; asm volatile("v_cvt_pk_bf16_f32 %0, %1, %2" : "=v"(r) : "v"(lo), "v"(hi)); return r; }
;     __device__ __forceinline__ void operator()(const f32x4 (&acc)[2][2][4][2], const Unit& u, int wr, int wc, int fr, int fq) const {
;     ...
;                 for (int m = 0; m < 4; ++m) { const size_t off = (size_t)(row0 + ai * HALF + m * 16) * 2048 + col0 + bj * HALF;
;                     if (isc) { *(f32x4*)(outC + off) = *(const f32x4*)(baseC + off) + g0 * acc[ai][bj][m][0]; *(f32x4*)(outC + off + 4) = *(const f32x4*)(baseC + off + 4) + g1 * acc[ai][bj][m][1]; }
;                     else { f32x4 b0, b1;
;                         if (BASE_BF16) { const u32x4 w = *(const u32x4*)(baseLb + off);
;                             b0 = (f32x4){__uint_as_float(w.x << 16), __uint_as_float(w.x & 0xffff0000u), __uint_as_float(w.y << 16), __uint_as_float(w.y & 0xffff0000u)};
;                             b1 = (f32x4){__uint_as_float(w.z << 16), __uint_as_float(w.z & 0xffff0000u), __uint_as_float(w.w << 16), __uint_as_float(w.w & 0xffff0000u)}; }
;                         else { b0 = *(const f32x4*)(baseLf + off); b1 = *(const f32x4*)(baseLf + off + 4); }
;                         const f32x4 o0 = b0 + g0 * acc[ai][bj][m][0], o1 = b1 + g1 * acc[ai][bj][m][1];
;                         u32x4 w; w.x = cvt_pk_bf16(o0[0], o0[1]); w.y = cvt_pk_bf16(o0[2], o0[3]); w.z = cvt_pk_bf16(o1[0], o1[1]); w.w = cvt_pk_bf16(o1[2], o1[3]);
;                         *(u32x4*)(outLb + off) = w; } } }
.LBB0_1373:
	v_lshlrev_b64 v[30:31], 1, v[24:25]
	v_lshl_add_u64 v[26:27], s[4:5], 0, v[30:31]
	v_mov_b32_e32 v26, v240
	v_mov_b32_e32 v27, v241
	v_mov_b32_e32 v28, v242
	v_mov_b32_e32 v29, v243
	v_lshl_add_u64 v[30:31], s[14:15], 0, v[30:31]
	v_lshlrev_b32_e32 v32, 16, v26
	v_and_b32_e32 v33, 0xffff0000, v26
	v_lshlrev_b32_e32 v26, 16, v27
	v_and_b32_e32 v27, 0xffff0000, v27
	v_lshlrev_b32_e32 v34, 16, v28
	v_and_b32_e32 v35, 0xffff0000, v28
	v_lshlrev_b32_e32 v28, 16, v29
	v_and_b32_e32 v29, 0xffff0000, v29
	v_pk_fma_f32 v[36:37], v[22:23], v[70:71], v[26:27]
	v_pk_fma_f32 v[26:27], v[20:21], v[68:69], v[32:33]
	v_pk_fma_f32 v[32:33], v[18:19], v[66:67], v[28:29]
	v_pk_fma_f32 v[28:29], v[16:17], v[64:65], v[34:35]
	v_cvt_pk_bf16_f32 v26, v26, v27
	v_cvt_pk_bf16_f32 v27, v36, v37
	s_nop 0
	v_cvt_pk_bf16_f32 v28, v28, v29
	v_cvt_pk_bf16_f32 v29, v32, v33
	global_store_dwordx4 v[30:31], v[26:29], off
	s_cbranch_execz .LBB0_1390

; __device__ __forceinline__ unsigned cvt_pk_bf16(float lo, float hi) { unsigned r; asm volatile("v_cvt_pk_bf16_f32 %0, %1, %2" : "=v"(r) : "v"(lo), "v"(hi)); return r; }
;     __device__ __forceinline__ void operator()(const f32x4 (&acc)[2][2][4][2], const Unit& u, int wr, int wc, int fr, int fq) const {
;     ...
;                 for (int m = 0; m < 4; ++m) { const size_t off = (size_t)(row0 + ai * HALF + m * 16) * 2048 + col0 + bj * HALF;
;                     if (isc) { *(f32x4*)(outC + off) = *(const f32x4*)(baseC + off) + g0 * acc[ai][bj][m][0]; *(f32x4*)(outC + off + 4) = *(const f32x4*)(baseC + off + 4) + g1 * acc[ai][bj][m][1]; }
;                     else { f32x4 b0, b1;
;                         if (BASE_BF16) { const u32x4 w = *(const u32x4*)(baseLb + off);
;                             b0 = (f32x4){__uint_as_float(w.x << 16), __uint_as_float(w.x & 0xffff0000u), __uint_as_float(w.y << 16), __uint_as_float(w.y & 0xffff0000u)};
;                             b1 = (f32x4){__uint_as_float(w.z << 16), __uint_as_float(w.z & 0xffff0000u), __uint_as_float(w.w << 16), __uint_as_float(w.w & 0xffff0000u)}; }
;                         else { b0 = *(const f32x4*)(baseLf + off); b1 = *(const f32x4*)(baseLf + off + 4); }
;                         const f32x4 o0 = b0 + g0 * acc[ai][bj][m][0], o1 = b1 + g1 * acc[ai][bj][m][1];
;                         u32x4 w; w.x = cvt_pk_bf16(o0[0], o0[1]); w.y = cvt_pk_bf16(o0[2], o0[3]); w.z = cvt_pk_bf16(o1[0], o1[1]); w.w = cvt_pk_bf16(o1[2], o1[3]);
;                         *(u32x4*)(outLb + off) = w; } } }
.LBB0_1375:
	v_lshlrev_b64 v[22:23], 1, v[16:17]
	v_lshl_add_u64 v[18:19], s[4:5], 0, v[22:23]
	v_mov_b32_e32 v18, v244
	v_mov_b32_e32 v19, v245
	v_mov_b32_e32 v20, v246
	v_mov_b32_e32 v21, v247
	v_lshl_add_u64 v[22:23], s[14:15], 0, v[22:23]
	v_lshlrev_b32_e32 v24, 16, v18
	v_and_b32_e32 v25, 0xffff0000, v18
	v_lshlrev_b32_e32 v18, 16, v19
	v_and_b32_e32 v19, 0xffff0000, v19
	v_lshlrev_b32_e32 v26, 16, v20
	v_and_b32_e32 v27, 0xffff0000, v20
	v_lshlrev_b32_e32 v20, 16, v21
	v_and_b32_e32 v21, 0xffff0000, v21
	v_pk_fma_f32 v[28:29], v[14:15], v[70:71], v[18:19]
	v_pk_fma_f32 v[18:19], v[12:13], v[68:69], v[24:25]
	v_pk_fma_f32 v[24:25], v[10:11], v[66:67], v[20:21]
	v_pk_fma_f32 v[20:21], v[8:9], v[64:65], v[26:27]
	v_cvt_pk_bf16_f32 v18, v18, v19
	v_cvt_pk_bf16_f32 v19, v28, v29
	s_nop 0
	v_cvt_pk_bf16_f32 v20, v20, v21
	v_cvt_pk_bf16_f32 v21, v24, v25
	global_store_dwordx4 v[22:23], v[18:21], off
	s_cbranch_execz .LBB0_1392

; __device__ __forceinline__ unsigned cvt_pk_bf16(float lo, float hi) { unsigned r; asm volatile("v_cvt_pk_bf16_f32 %0, %1, %2" : "=v"(r) : "v"(lo), "v"(hi)); return r; }
;     __device__ __forceinline__ void operator()(const f32x4 (&acc)[2][2][4][2], const Unit& u, int wr, int wc, int fr, int fq) const {
;     ...
;                 for (int m = 0; m < 4; ++m) { const size_t off = (size_t)(row0 + ai * HALF + m * 16) * 2048 + col0 + bj * HALF;
;                     if (isc) { *(f32x4*)(outC + off) = *(const f32x4*)(baseC + off) + g0 * acc[ai][bj][m][0]; *(f32x4*)(outC + off + 4) = *(const f32x4*)(baseC + off + 4) + g1 * acc[ai][bj][m][1]; }
;                     else { f32x4 b0, b1;
;                         if (BASE_BF16) { const u32x4 w = *(const u32x4*)(baseLb + off);
;                             b0 = (f32x4){__uint_as_float(w.x << 16), __uint_as_float(w.x & 0xffff0000u), __uint_as_float(w.y << 16), __uint_as_float(w.y & 0xffff0000u)};
;                             b1 = (f32x4){__uint_as_float(w.z << 16), __uint_as_float(w.z & 0xffff0000u), __uint_as_float(w.w << 16), __uint_as_float(w.w & 0xffff0000u)}; }
;                         else { b0 = *(const f32x4*)(baseLf + off); b1 = *(const f32x4*)(baseLf + off + 4); }
;                         const f32x4 o0 = b0 + g0 * acc[ai][bj][m][0], o1 = b1 + g1 * acc[ai][bj][m][1];
;                         u32x4 w; w.x = cvt_pk_bf16(o0[0], o0[1]); w.y = cvt_pk_bf16(o0[2], o0[3]); w.z = cvt_pk_bf16(o1[0], o1[1]); w.w = cvt_pk_bf16(o1[2], o1[3]);
;                         *(u32x4*)(outLb + off) = w; } } }
.LBB0_1377:
	v_lshlrev_b64 v[14:15], 1, v[8:9]
	v_lshl_add_u64 v[10:11], s[4:5], 0, v[14:15]
	v_mov_b32_e32 v10, v248
	v_mov_b32_e32 v11, v249
	v_mov_b32_e32 v12, v250
	v_mov_b32_e32 v13, v251
	v_lshl_add_u64 v[14:15], s[14:15], 0, v[14:15]
	v_lshlrev_b32_e32 v16, 16, v10
	v_and_b32_e32 v17, 0xffff0000, v10
	v_lshlrev_b32_e32 v10, 16, v11
	v_and_b32_e32 v11, 0xffff0000, v11
	v_lshlrev_b32_e32 v18, 16, v12
	v_and_b32_e32 v19, 0xffff0000, v12
	v_lshlrev_b32_e32 v12, 16, v13
	v_and_b32_e32 v13, 0xffff0000, v13
	v_pk_fma_f32 v[20:21], v[6:7], v[70:71], v[10:11]
	v_pk_fma_f32 v[10:11], v[4:5], v[68:69], v[16:17]
	v_pk_fma_f32 v[16:17], v[2:3], v[66:67], v[12:13]
	v_pk_fma_f32 v[12:13], v[0:1], v[64:65], v[18:19]
	v_cvt_pk_bf16_f32 v10, v10, v11
	v_cvt_pk_bf16_f32 v11, v20, v21
	s_nop 0
	v_cvt_pk_bf16_f32 v12, v12, v13
	v_cvt_pk_bf16_f32 v13, v16, v17
	global_store_dwordx4 v[14:15], v[10:13], off
	s_cbranch_execz .LBB0_1394

; __global__ void __launch_bounds__(512, 2) fwd_megakernel(Args a) {
	.amdhsa_kernel _Z14fwd_megakernel4Args
		.amdhsa_group_segment_fixed_size 0
		.amdhsa_private_segment_fixed_size 0
		.amdhsa_kernarg_size 592
		.amdhsa_user_sgpr_count 2
		.amdhsa_user_sgpr_dispatch_ptr 0
		.amdhsa_user_sgpr_queue_ptr 0
		.amdhsa_user_sgpr_kernarg_segment_ptr 1
		.amdhsa_user_sgpr_dispatch_id 0
		.amdhsa_user_sgpr_kernarg_preload_length 0
		.amdhsa_user_sgpr_kernarg_preload_offset 0
		.amdhsa_user_sgpr_private_segment_size 0
		.amdhsa_uses_dynamic_stack 0
		.amdhsa_enable_private_segment 0
		.amdhsa_system_sgpr_workgroup_id_x 1
		.amdhsa_system_sgpr_workgroup_id_y 0
		.amdhsa_system_sgpr_workgroup_id_z 0
		.amdhsa_system_sgpr_workgroup_info 0
		.amdhsa_system_vgpr_workitem_id 2
		.amdhsa_next_free_vgpr 256
		.amdhsa_next_free_sgpr 102
		.amdhsa_accum_offset 256
		.amdhsa_reserve_vcc 1
		.amdhsa_float_round_mode_32 0
		.amdhsa_float_round_mode_16_64 0
		.amdhsa_float_denorm_mode_32 3
		.amdhsa_float_denorm_mode_16_64 3
		.amdhsa_dx10_clamp 1
		.amdhsa_ieee_mode 1
		.amdhsa_fp16_overflow 0
		.amdhsa_tg_split 0
		.amdhsa_exception_fp_ieee_invalid_op 0
		.amdhsa_exception_fp_denorm_src 0
		.amdhsa_exception_fp_ieee_div_zero 0
		.amdhsa_exception_fp_ieee_overflow 0
		.amdhsa_exception_fp_ieee_underflow 0
		.amdhsa_exception_fp_ieee_inexact 0
		.amdhsa_exception_int_div_zero 0
	.end_amdhsa_kernel

; __global__ void __launch_bounds__(512, 2) fwd_megakernel(Args a) {
amdhsa.kernels:
  - .agpr_count:     0
    .args:
      - .offset:         0
        .size:           336
        .value_kind:     by_value
      - .offset:         336
        .size:           4
        .value_kind:     hidden_block_count_x
      - .offset:         340
        .size:           4
        .value_kind:     hidden_block_count_y
      - .offset:         344
        .size:           4
        .value_kind:     hidden_block_count_z
      - .offset:         348
        .size:           2
        .value_kind:     hidden_group_size_x
      - .offset:         350
        .size:           2
        .value_kind:     hidden_group_size_y
      - .offset:         352
        .size:           2
        .value_kind:     hidden_group_size_z
      - .offset:         354
        .size:           2
        .value_kind:     hidden_remainder_x
      - .offset:         356
        .size:           2
        .value_kind:     hidden_remainder_y
      - .offset:         358
        .size:           2
        .value_kind:     hidden_remainder_z
      - .offset:         376
        .size:           8
        .value_kind:     hidden_global_offset_x
      - .offset:         384
        .size:           8
        .value_kind:     hidden_global_offset_y
      - .offset:         392
        .size:           8
        .value_kind:     hidden_global_offset_z
      - .offset:         400
        .size:           2
        .value_kind:     hidden_grid_dims
      - .offset:         424
        .size:           8
        .value_kind:     hidden_multigrid_sync_arg
      - .offset:         456
        .size:           4
        .value_kind:     hidden_dynamic_lds_size
    .group_segment_fixed_size: 0
    .kernarg_segment_align: 8
    .kernarg_segment_size: 592
    .language:       OpenCL C
    .language_version:
      - 2
      - 0
    .max_flat_workgroup_size: 512
    .name:           _Z14fwd_megakernel4Args
    .private_segment_fixed_size: 0
    .sgpr_count:     108
    .sgpr_spill_count: 125
    .symbol:         _Z14fwd_megakernel4Args.kd
    .uniform_work_group_size: 1
    .uses_dynamic_stack: false
    .vgpr_count:     256
    .vgpr_spill_count: 0
    .wavefront_size: 64
